# stack42 with s_sleep 3 instead of s_sleep 1 in the grid-barrier polling loops (looser polling)
# speedup vs baseline: 1.0027x; 1.0027x over previous
.LBB0_10:
	s_sleep 3
	global_load_dword v2, v1, s[4:5] offset:32 sc1
	s_waitcnt vmcnt(0)
	v_and_b32_e32 v2, 0xffff0000, v2
	v_cmp_ne_u32_e32 vcc, v2, v0
	s_or_b64 s[6:7], vcc, s[6:7]
	s_andn2_b64 exec, exec, s[6:7]
	s_cbranch_execnz .LBB0_10

.LBB0_98:
	global_load_dword v15, v16, s[12:13] sc1
	global_load_dword v0, v16, s[14:15] sc1
	global_load_dword v1, v16, s[16:17] sc1
	global_load_dword v2, v16, s[18:19] sc1
	global_load_dword v3, v16, s[28:29] sc1
	global_load_dword v4, v16, s[30:31] sc1
	global_load_dword v5, v16, s[34:35] sc1
	global_load_dword v6, v16, s[36:37] sc1
	global_load_dword v7, v16, s[38:39] sc1
	global_load_dword v8, v16, s[40:41] sc1
	global_load_dword v9, v16, s[42:43] sc1
	global_load_dword v10, v16, s[44:45] sc1
	global_load_dword v11, v16, s[46:47] sc1
	global_load_dword v12, v16, s[48:49] sc1
	global_load_dword v13, v16, s[50:51] sc1
	global_load_dword v14, v16, s[52:53] sc1
	s_mov_b64 s[54:55], -1
	s_mov_b64 s[56:57], -1
	s_waitcnt vmcnt(14)
	v_add_u32_e32 v17, v0, v15
	s_waitcnt vmcnt(13)
	v_add_u32_e32 v17, v17, v1
	s_waitcnt vmcnt(12)
	v_add_u32_e32 v17, v17, v2
	s_waitcnt vmcnt(11)
	v_add_u32_e32 v17, v17, v3
	s_waitcnt vmcnt(10)
	v_add_u32_e32 v17, v17, v4
	s_waitcnt vmcnt(9)
	v_add_u32_e32 v17, v17, v5
	s_waitcnt vmcnt(8)
	v_add_u32_e32 v17, v17, v6
	s_waitcnt vmcnt(7)
	v_add_u32_e32 v17, v17, v7
	s_waitcnt vmcnt(6)
	v_add_u32_e32 v17, v17, v8
	s_waitcnt vmcnt(5)
	v_add_u32_e32 v17, v17, v9
	s_waitcnt vmcnt(4)
	v_add_u32_e32 v17, v17, v10
	s_waitcnt vmcnt(3)
	v_add_u32_e32 v17, v17, v11
	s_waitcnt vmcnt(2)
	v_add_u32_e32 v17, v17, v12
	s_waitcnt vmcnt(1)
	v_add_u32_e32 v17, v17, v13
	s_waitcnt vmcnt(0)
	v_add_u32_e32 v17, v17, v14
	v_cmp_eq_u32_e32 vcc, s21, v17
	s_cbranch_vccnz .LBB0_97
	s_and_b32 s24, s23, 0xff
	s_cmp_eq_u32 s24, 0
	s_mov_b64 s[58:59], -1
	s_sleep 3
	s_cbranch_scc0 .LBB0_102
	global_load_dword v17, v16, s[8:9] sc1
	s_waitcnt vmcnt(0)
	v_cmp_eq_u32_e32 vcc, 0, v17
	s_cbranch_vccnz .LBB0_104
	s_mov_b64 s[58:59], 0

.LBB0_116:
	s_and_b32 s21, s11, 0xff
	s_mov_b64 s[34:35], -1
	s_cmp_lg_u32 s21, 0
	s_mov_b64 s[38:39], -1
	s_sleep 3
	s_cbranch_scc1 .LBB0_119
	global_load_dword v2, v0, s[16:17] sc1
	s_waitcnt vmcnt(0)
	v_cmp_eq_u32_e32 vcc, 0, v2
	s_cbranch_vccnz .LBB0_121
	s_mov_b64 s[38:39], 0
	s_mov_b64 s[36:37], -1

.LBB0_133:
	s_and_b32 s21, s11, 0xff
	s_cmp_lg_u32 s21, 0
	s_mov_b64 s[34:35], -1
	s_sleep 3
	s_cbranch_scc1 .LBB0_136
	global_load_dword v1, v0, s[16:17] sc1
	s_waitcnt vmcnt(0)
	v_cmp_eq_u32_e32 vcc, 0, v1
	s_cbranch_vccnz .LBB0_138
	s_mov_b64 s[34:35], 0
	s_mov_b64 s[30:31], -1

.LBB0_1343:
	global_load_dword v15, v16, s[10:11] sc1
	global_load_dword v0, v16, s[12:13] sc1
	global_load_dword v1, v16, s[14:15] sc1
	global_load_dword v2, v16, s[16:17] sc1
	global_load_dword v3, v16, s[18:19] sc1
	global_load_dword v4, v16, s[26:27] sc1
	global_load_dword v5, v16, s[28:29] sc1
	global_load_dword v6, v16, s[30:31] sc1
	global_load_dword v7, v16, s[34:35] sc1
	global_load_dword v8, v16, s[36:37] sc1
	global_load_dword v9, v16, s[38:39] sc1
	global_load_dword v10, v16, s[40:41] sc1
	global_load_dword v11, v16, s[42:43] sc1
	global_load_dword v12, v16, s[44:45] sc1
	global_load_dword v13, v16, s[46:47] sc1
	global_load_dword v14, v16, s[48:49] sc1
	s_mov_b64 s[50:51], -1
	s_mov_b64 s[52:53], -1
	s_waitcnt vmcnt(14)
	v_add_u32_e32 v17, v0, v15
	s_waitcnt vmcnt(13)
	v_add_u32_e32 v17, v17, v1
	s_waitcnt vmcnt(12)
	v_add_u32_e32 v17, v17, v2
	s_waitcnt vmcnt(11)
	v_add_u32_e32 v17, v17, v3
	s_waitcnt vmcnt(10)
	v_add_u32_e32 v17, v17, v4
	s_waitcnt vmcnt(9)
	v_add_u32_e32 v17, v17, v5
	s_waitcnt vmcnt(8)
	v_add_u32_e32 v17, v17, v6
	s_waitcnt vmcnt(7)
	v_add_u32_e32 v17, v17, v7
	s_waitcnt vmcnt(6)
	v_add_u32_e32 v17, v17, v8
	s_waitcnt vmcnt(5)
	v_add_u32_e32 v17, v17, v9
	s_waitcnt vmcnt(4)
	v_add_u32_e32 v17, v17, v10
	s_waitcnt vmcnt(3)
	v_add_u32_e32 v17, v17, v11
	s_waitcnt vmcnt(2)
	v_add_u32_e32 v17, v17, v12
	s_waitcnt vmcnt(1)
	v_add_u32_e32 v17, v17, v13
	s_waitcnt vmcnt(0)
	v_add_u32_e32 v17, v17, v14
	v_cmp_eq_u32_e32 vcc, s23, v17
	s_cbranch_vccnz .LBB0_1342
	s_and_b32 s25, s24, 0xff
	s_cmp_eq_u32 s25, 0
	s_mov_b64 s[54:55], -1
	s_sleep 3
	s_cbranch_scc0 .LBB0_1347
	global_load_dword v17, v16, s[8:9] sc1
	s_waitcnt vmcnt(0)
	v_cmp_eq_u32_e32 vcc, 0, v17
	s_cbranch_vccnz .LBB0_1349
	s_mov_b64 s[54:55], 0

.LBB0_1361:
	s_and_b32 s23, s21, 0xff
	s_mov_b64 s[28:29], -1
	s_cmp_lg_u32 s23, 0
	s_mov_b64 s[34:35], -1
	s_sleep 3
	s_cbranch_scc1 .LBB0_1364
	global_load_dword v2, v0, s[14:15] sc1
	s_waitcnt vmcnt(0)
	v_cmp_eq_u32_e32 vcc, 0, v2
	s_cbranch_vccnz .LBB0_1366
	s_mov_b64 s[34:35], 0
	s_mov_b64 s[30:31], -1

.LBB0_1378:
	s_and_b32 s23, s21, 0xff
	s_cmp_lg_u32 s23, 0
	s_mov_b64 s[28:29], -1
	s_sleep 3
	s_cbranch_scc1 .LBB0_1381
	global_load_dword v1, v0, s[14:15] sc1
	s_waitcnt vmcnt(0)
	v_cmp_eq_u32_e32 vcc, 0, v1
	s_cbranch_vccnz .LBB0_1383
	s_mov_b64 s[28:29], 0
	s_mov_b64 s[26:27], -1
